# v66 + s=0 norm1 loop: gain in registers, adaLN shift/scale in LDS, load/wait chains removed (X-store WAR padded)
# speedup vs baseline: 1.0004x; 1.0004x over previous
.LBB0_814:
	v_lshlrev_b64 v[0:1], 12, v[0:1]
	v_lshl_add_u64 v[4:5], v[4:5], 0, v[0:1]
	v_lshlrev_b32_e32 v0, 2, v21
	v_and_b32_e32 v0, 0xfc, v0
	v_lshlrev_b32_e32 v22, 2, v0
	v_mov_b32_e32 v23, v2
	v_lshl_add_u64 v[4:5], v[4:5], 0, v[22:23]
	global_load_dwordx4 v[16:19], v[4:5], off
	global_load_dwordx4 v[12:15], v[4:5], off offset:1024
	global_load_dwordx4 v[8:11], v[4:5], off offset:2048
	s_nop 0
	global_load_dwordx4 v[4:7], v[4:5], off offset:3072
	v_cmp_lt_i32_e32 vcc, v180, v182
	v_readlane_b32 s2, v255, 0
	v_readlane_b32 s3, v255, 1
	v_cndmask_b32_e32 v1, v179, v180, vcc
	v_cmp_lt_i32_e32 vcc, v183, v182
	v_lshl_add_u64 v[36:37], s[2:3], 0, v[22:23]
	global_load_dwordx4 v[100:103], v[36:37], off
	global_load_dwordx4 v[104:107], v[36:37], off offset:1024
	global_load_dwordx4 v[108:111], v[36:37], off offset:2048
	global_load_dwordx4 v[112:115], v[36:37], off offset:3072
	v_lshlrev_b64 v[22:23], 11, v[42:43]
	v_cndmask_b32_e32 v3, v179, v183, vcc
	v_cmp_lt_i32_e32 vcc, v184, v182
	v_and_b32_e32 v25, 63, v21
	v_readlane_b32 s2, v252, 32
	v_cndmask_b32_e32 v24, v179, v184, vcc
	v_cmp_lt_i32_e32 vcc, v185, v182
	v_lshlrev_b32_e32 v58, 2, v24
	v_lshl_or_b32 v22, v25, 3, v22
	v_cndmask_b32_e32 v24, v179, v185, vcc
	v_cmp_lt_i32_e32 vcc, v186, v182
	v_readlane_b32 s3, v252, 33
	v_lshlrev_b32_e32 v59, 2, v24
	v_cndmask_b32_e32 v24, v179, v186, vcc
	v_cmp_lt_i32_e32 vcc, v187, v182
	v_lshl_add_u64 v[38:39], s[2:3], 0, v[22:23]
	v_readlane_b32 s2, v254, 2
	v_lshlrev_b32_e32 v60, 2, v24
	v_cndmask_b32_e32 v24, v179, v187, vcc
	v_add_u32_e32 v40, s2, v20
	v_lshlrev_b64 v[20:21], 12, v[42:43]
	v_readlane_b32 s2, v254, 24
	v_lshlrev_b32_e32 v61, 2, v24
	v_or_b32_e32 v24, 0x100, v0
	v_or_b32_e32 v26, 0x200, v0
	v_or_b32_e32 v28, 0x300, v0
	v_lshl_or_b32 v20, v25, 4, v20
	v_readlane_b32 s3, v254, 25
	v_lshlrev_b32_e32 v1, 2, v1
	v_lshlrev_b32_e32 v3, 2, v3
	v_ashrrev_i32_e32 v41, 31, v40
	v_lshl_add_u64 v[44:45], s[2:3], 0, v[20:21]
	s_mov_b64 s[44:45], 0
	v_lshlrev_b32_e32 v46, 2, v24
	v_lshlrev_b32_e32 v48, 2, v26
	v_lshlrev_b32_e32 v50, 2, v28
	v_lshlrev_b32_e32 v156, 4, v168
	v_add_u32_e32 v158, 0x1000, v156
	v_readlane_b32 s20, v251, 63
	v_readlane_b32 s21, v252, 0
	v_readlane_b32 vcc_lo, v254, 61
	s_mul_i32 vcc_lo, vcc_lo, 0x1e000
	s_add_u32 s20, s20, vcc_lo
	s_addc_u32 s21, s21, 0
	global_load_dwordx4 v[116:119], v156, s[20:21]
	global_load_dwordx4 v[120:123], v158, s[20:21]
	s_add_u32 s20, s20, 0x6000
	s_addc_u32 s21, s21, 0
	global_load_dwordx4 v[124:127], v156, s[20:21]
	global_load_dwordx4 v[128:131], v158, s[20:21]
	s_add_u32 s20, s20, 0x6000
	s_addc_u32 s21, s21, 0
	global_load_dwordx4 v[132:135], v156, s[20:21]
	global_load_dwordx4 v[136:139], v158, s[20:21]
	s_add_u32 s20, s20, 0x6000
	s_addc_u32 s21, s21, 0
	global_load_dwordx4 v[140:143], v156, s[20:21]
	global_load_dwordx4 v[144:147], v158, s[20:21]
	s_add_u32 s20, s20, 0x6000
	s_addc_u32 s21, s21, 0
	global_load_dwordx4 v[148:151], v156, s[20:21]
	global_load_dwordx4 v[152:155], v158, s[20:21]
	s_waitcnt vmcnt(0)
	ds_write_b128 v156, v[116:119]
	ds_write_b128 v156, v[120:123] offset:4096
	ds_write_b128 v156, v[124:127] offset:8192
	ds_write_b128 v156, v[128:131] offset:12288
	ds_write_b128 v156, v[132:135] offset:16384
	ds_write_b128 v156, v[136:139] offset:20480
	ds_write_b128 v156, v[140:143] offset:24576
	ds_write_b128 v156, v[144:147] offset:28672
	ds_write_b128 v156, v[148:151] offset:32768
	ds_write_b128 v156, v[152:155] offset:36864
	s_waitcnt lgkmcnt(0)
	s_barrier
	s_branch .LBB0_816
.LBB0_815:
	v_readlane_b32 s2, v254, 11
	v_readlane_b32 s3, v254, 12
	v_cmp_lt_i32_e32 vcc, s35, v52
	v_lshl_add_u64 v[40:41], v[40:41], 0, s[0:1]
	v_lshl_add_u64 v[38:39], v[38:39], 0, s[2:3]
	v_readlane_b32 s2, v254, 9
	v_readlane_b32 s3, v254, 10
	s_or_b64 s[44:45], vcc, s[44:45]
	v_mov_b32_e32 v42, v52
	v_lshl_add_u64 v[44:45], v[44:45], 0, s[2:3]
	s_waitcnt vmcnt(4)
	v_mov_b32_e32 v16, v32
	v_mov_b32_e32 v17, v33
	v_mov_b32_e32 v18, v34
	v_mov_b32_e32 v19, v35
	v_mov_b32_e32 v12, v28
	v_mov_b32_e32 v13, v29
	v_mov_b32_e32 v14, v30
	v_mov_b32_e32 v15, v31
	v_mov_b32_e32 v8, v24
	v_mov_b32_e32 v9, v25
	v_mov_b32_e32 v10, v26
	v_mov_b32_e32 v11, v27
	v_mov_b32_e32 v4, v20
	v_mov_b32_e32 v5, v21
	v_mov_b32_e32 v6, v22
	v_mov_b32_e32 v7, v23
	s_andn2_b64 exec, exec, s[44:45]
	s_cbranch_execz .LBB0_832

.LBB0_824:
	s_or_b64 exec, exec, s[36:37]
	v_add_u32_e32 v43, 0xfffff000, v42
	v_lshrrev_b32_e32 v43, 11, v43
	s_movk_i32 s2, 0xfff
	v_add_u32_e32 v43, 1, v43
	v_cmp_lt_i32_e32 vcc, s2, v42
	v_readlane_b32 s2, v254, 60
	v_lshlrev_b32_e32 v56, 2, v0
	v_cndmask_b32_e32 v42, 0, v43, vcc
	v_lshl_add_u32 v157, v42, 13, v56
	ds_read_b128 v[116:119], v157
	ds_read_b128 v[120:123], v157 offset:1024
	ds_read_b128 v[124:127], v157 offset:2048
	ds_read_b128 v[128:131], v157 offset:3072
	ds_read_b128 v[132:135], v157 offset:4096
	ds_read_b128 v[136:139], v157 offset:5120
	ds_read_b128 v[140:143], v157 offset:6144
	ds_read_b128 v[144:147], v157 offset:7168
	v_add_u32_e32 v47, s2, v42
	v_readlane_b32 s2, v251, 63
	v_readlane_b32 s3, v252, 0
	v_mov_b32_e32 v57, v2
	v_mov_b64_e32 v[42:43], s[2:3]
	v_mad_i64_i32 v[54:55], s[20:21], v47, s97, v[42:43]
	s_mov_b64 s[2:3], 0x1000
	v_lshl_add_u64 v[42:43], v[54:55], 0, s[2:3]
	v_lshl_add_u64 v[66:67], v[42:43], 0, v[56:57]
	v_lshl_add_u64 v[54:55], v[54:55], 0, v[56:57]
	v_mul_f32_e32 v47, v17, v17
	v_mul_f32_e32 v49, v13, v13
	v_mul_f32_e32 v51, v9, v9
	v_fmac_f32_e32 v47, v16, v16
	v_fmac_f32_e32 v49, v12, v12
	v_mul_f32_e32 v53, v5, v5
	v_fmac_f32_e32 v51, v8, v8
	v_fmac_f32_e32 v47, v18, v18
	v_fmac_f32_e32 v49, v14, v14
	v_fmac_f32_e32 v53, v4, v4
	v_fmac_f32_e32 v51, v10, v10
	v_fmac_f32_e32 v47, v19, v19
	v_fmac_f32_e32 v49, v15, v15
	v_fmac_f32_e32 v53, v6, v6
	v_fmac_f32_e32 v51, v11, v11
	v_add_f32_e32 v47, v47, v49
	v_fmac_f32_e32 v53, v7, v7
	v_add_f32_e32 v47, v51, v47
	v_add_f32_e32 v47, v53, v47
	ds_bpermute_b32 v49, v1, v47
	s_andn2_b64 vcc, exec, s[40:41]
	s_waitcnt lgkmcnt(0)
	v_add_f32_e32 v47, v47, v49
	ds_bpermute_b32 v49, v3, v47
	s_waitcnt lgkmcnt(0)
	v_add_f32_e32 v47, v47, v49
	ds_bpermute_b32 v49, v58, v47
	s_waitcnt lgkmcnt(0)
	v_add_f32_e32 v47, v47, v49
	ds_bpermute_b32 v49, v59, v47
	s_waitcnt lgkmcnt(0)
	v_add_f32_e32 v47, v47, v49
	ds_bpermute_b32 v49, v60, v47
	s_waitcnt lgkmcnt(0)
	v_add_f32_e32 v47, v47, v49
	ds_bpermute_b32 v49, v61, v47
	s_waitcnt lgkmcnt(0)
	v_add_f32_e32 v47, v47, v49
	v_fmamk_f32 v47, v47, 0x3a800000, v174
	v_rsq_f32_e32 v56, v47
	v_cndmask_b32_e64 v47, 0, 1, s[40:41]
	v_cmp_ne_u32_e64 s[36:37], 1, v47
	v_pk_mul_f32 v[74:75], v[18:19], v[56:57] op_sel_hi:[1,0]
	v_pk_mul_f32 v[76:77], v[16:17], v[56:57] op_sel_hi:[1,0]
	v_pk_mul_f32 v[64:65], v[102:103], v[74:75]
	v_pk_mul_f32 v[62:63], v[100:101], v[76:77]
	v_pk_add_f32 v[68:69], v[134:135], 1.0 op_sel_hi:[1,0]
	v_pk_add_f32 v[66:67], v[132:133], 1.0 op_sel_hi:[1,0]
	v_pk_fma_f32 v[64:65], v[68:69], v[64:65], v[118:119]
	v_pk_fma_f32 v[62:63], v[66:67], v[62:63], v[116:117]
	s_nop 0
	v_cvt_pk_bf16_f32 v62, v62, v63
	v_cvt_pk_bf16_f32 v63, v64, v65
	global_store_dwordx2 v[38:39], v[62:63], off
	s_cbranch_vccnz .LBB0_826
	global_store_dwordx4 v[44:45], v[16:19], off offset:-2048
	s_nop 1
.LBB0_826:
	v_mov_b32_e32 v47, v2
	v_lshl_add_u64 v[16:17], v[42:43], 0, v[46:47]
	v_mov_b32_e32 v57, v56
	v_mov_b32_e32 v16, v56
	v_mov_b32_e32 v17, v56
	v_pk_mul_f32 v[18:19], v[14:15], v[16:17]
	v_pk_mul_f32 v[74:75], v[12:13], v[56:57]
	s_and_b64 vcc, exec, s[36:37]
	v_pk_mul_f32 v[18:19], v[18:19], v[106:107]
	v_pk_mul_f32 v[62:63], v[74:75], v[104:105]
	v_pk_add_f32 v[64:65], v[138:139], 1.0 op_sel_hi:[1,0]
	v_pk_add_f32 v[66:67], v[136:137], 1.0 op_sel_hi:[1,0]
	v_pk_fma_f32 v[18:19], v[18:19], v[64:65], v[122:123]
	v_pk_fma_f32 v[62:63], v[62:63], v[66:67], v[120:121]
	s_nop 0
	v_cvt_pk_bf16_f32 v62, v62, v63
	v_cvt_pk_bf16_f32 v63, v18, v19
	global_store_dwordx2 v[38:39], v[62:63], off offset:512
	s_cbranch_vccnz .LBB0_828
	global_store_dwordx4 v[44:45], v[12:15], off offset:-1024
	s_nop 1
.LBB0_828:
	v_mov_b32_e32 v49, v2
	v_lshl_add_u64 v[18:19], v[42:43], 0, v[48:49]
	v_pk_mul_f32 v[16:17], v[10:11], v[16:17]
	v_pk_mul_f32 v[18:19], v[8:9], v[56:57]
	s_and_b64 vcc, exec, s[36:37]
	v_pk_mul_f32 v[14:15], v[16:17], v[110:111]
	v_pk_mul_f32 v[12:13], v[18:19], v[108:109]
	v_pk_add_f32 v[16:17], v[142:143], 1.0 op_sel_hi:[1,0]
	v_pk_add_f32 v[18:19], v[140:141], 1.0 op_sel_hi:[1,0]
	v_pk_fma_f32 v[14:15], v[14:15], v[16:17], v[126:127]
	v_pk_fma_f32 v[12:13], v[12:13], v[18:19], v[124:125]
	s_nop 0
	v_cvt_pk_bf16_f32 v12, v12, v13
	v_cvt_pk_bf16_f32 v13, v14, v15
	global_store_dwordx2 v[38:39], v[12:13], off offset:1024
	s_cbranch_vccnz .LBB0_830
	global_store_dwordx4 v[44:45], v[8:11], off
	s_nop 1
.LBB0_830:
	v_mov_b32_e32 v51, v2
	v_lshl_add_u64 v[12:13], v[42:43], 0, v[50:51]
	s_nop 0
	v_mov_b32_e32 v42, v56
	v_mov_b32_e32 v43, v56
	v_pk_mul_f32 v[54:55], v[4:5], v[56:57]
	v_pk_mul_f32 v[42:43], v[6:7], v[42:43]
	s_and_b64 vcc, exec, s[36:37]
	v_pk_mul_f32 v[10:11], v[42:43], v[114:115]
	v_pk_mul_f32 v[8:9], v[54:55], v[112:113]
	v_pk_add_f32 v[14:15], v[146:147], 1.0 op_sel_hi:[1,0]
	v_pk_add_f32 v[12:13], v[144:145], 1.0 op_sel_hi:[1,0]
	v_pk_fma_f32 v[10:11], v[10:11], v[14:15], v[130:131]
	v_pk_fma_f32 v[8:9], v[8:9], v[12:13], v[128:129]
	s_nop 0
	v_cvt_pk_bf16_f32 v8, v8, v9
	v_cvt_pk_bf16_f32 v9, v10, v11
	global_store_dwordx2 v[38:39], v[8:9], off offset:1536
	s_cbranch_vccnz .LBB0_815
	global_store_dwordx4 v[44:45], v[4:7], off offset:1024
	s_nop 1
	s_branch .LBB0_815
